# P5 tail balance: a_w_out conversion moved to the waves without a second chunk-weight item
# speedup vs baseline: 1.0061x; 1.0041x over previous
.LBB0_673:
	s_addk_i32 s30, 0xfc00
	s_cmp_lt_i32 s30, 0
	s_cbranch_scc1 .LBB0_676
	v_and_b32_e32 v3, 56, v5
	s_load_dwordx2 s[4:5], s[18:19], 0x30
	v_mov_b32_e32 v7, 0
	v_lshlrev_b32_e32 v6, 1, v3
	v_lshl_add_u64 v[8:9], s[16:17], 0, v[6:7]
	s_mov_b64 s[6:7], 0x1600000
	v_lshl_add_u32 v13, v4, 2, s31
	v_mul_u32_u24_e32 v14, 0x84, v2
	v_lshl_add_u64 v[8:9], v[8:9], 0, s[6:7]
	s_lshl_b32 s6, s2, 4
	s_lshl_b32 s7, s54, 1
	v_mul_u32_u24_e32 v5, 0x84, v3
	v_lshlrev_b32_e32 v3, 2, v46
	s_add_i32 s10, s6, s7
	s_addk_i32 s10, 0xf800
	s_lshl_b32 s6, s2, 8
	s_lshl_b32 s7, s54, 5
	v_add_u32_e32 v13, v13, v14
	v_add3_u32 v3, s31, v5, v3
	v_or_b32_e32 v10, 8, v46
	v_or_b32_e32 v11, 16, v46
	v_or_b32_e32 v12, 24, v46
	s_lshl_b32 s11, s52, 4
	s_add_i32 s12, s6, s7
	s_lshl_b32 s13, s52, 8
	s_mov_b32 s7, 0
	v_lshlrev_b32_e32 v4, 2, v4
	v_mov_b32_e32 v5, v7
	v_add_u32_e32 v14, 0x400, v13
	v_add_u32_e32 v15, 0x800, v13
	v_add_u32_e32 v16, 0xc00, v13
	v_add_u32_e32 v17, 0x1000, v13
	s_waitcnt vmcnt(0)
	v_add_u32_e32 v18, 0x1400, v13
	v_add_u32_e32 v19, 0x1800, v13
	v_add_u32_e32 v20, 0x1c00, v13
